# attention fast loop: dead SALU ring-slot arithmetic removed from the barrier-to-first-read path
# speedup vs baseline: 1.0078x; 1.0003x over previous
; __device__ __forceinline__ void finishSM(f32x16& p0, f32x16& p1, float alpha, float& l_reg, bf16x8& pa0, bf16x8& pa1, bf16x8& pa2, bf16x8& pa3) {
; #pragma unroll
;   for (int r = 0; r < 16; ++r) p1[r] = __builtin_amdgcn_exp2f(p1[r]);
;   float ps = 0;
; #pragma unroll
;   for (int r = 0; r < 16; ++r) ps += p0[r];
; #pragma unroll
;   for (int r = 0; r < 16; ++r) ps += p1[r];
;   { auto rr = __builtin_amdgcn_permlane32_swap(__float_as_uint(ps), __float_as_uint(ps), false, false);
;     ps = __uint_as_float(rr[0]) + __uint_as_float(rr[1]); }
;   l_reg = l_reg * alpha + ps;
;     ...
;   PK4(p0, 0, pa0); PK4(p0, 8, pa1); PK4(p1, 0, pa2); PK4(p1, 8, pa3);
;     ...
; }
; __device__ __forceinline__ void qkt(f32x16& p0, f32x16& p1, const char* Ks, const bf16x8* qr, const f32x16& negm, int r32, int hi) {
;   p0 = negm; p1 = negm;
; #pragma unroll
;   for (int d0 = 0; d0 < 6; ++d0) { int cb = (d0 * 16 + hi * 8) * 2;
;     bf16x8 b0 = *reinterpret_cast<const bf16x8*>(Ks + KSWZ(r32, cb));
;     bf16x8 b1 = *reinterpret_cast<const bf16x8*>(Ks + KSWZ(32 + r32, cb));
;     p0 = __builtin_amdgcn_mfma_f32_32x32x16_bf16(b0, qr[d0], p0, 0, 0, 0);
;     p1 = __builtin_amdgcn_mfma_f32_32x32x16_bf16(b1, qr[d0], p1, 0, 0, 0); }
; }
; __device__ __forceinline__ int v_st(int k, int c) { const int kk = k; return ((kk >> 3) * 4 + (c >> 5)) * 512 + ((kk & 7) * 32 + (c & 31)) * 2; }
; __device__ __forceinline__ int v_rd_base(int lane) { return ((lane & 3) << 3) | (((lane >> 2) & 3) << 6) | (((lane >> 4) & 1) << 5) | (((lane >> 5) & 1) << 8); }
; __device__ __forceinline__ s16x4 vtr(lds_cptr p) { return __builtin_bit_cast(s16x4, __builtin_amdgcn_ds_read_tr16_b64_v4i16((LAS v4i16_t*)p)); }
; template <int D0> __device__ __forceinline__ void pv_one(f32x16& od, lds_cptr vp, bf16x8 pa0, bf16x8 pa1, bf16x8 pa2, bf16x8 pa3) {
;   const s16x4 l0 = vtr(vp + v_rd_off(D0, 0, 0)), h0 = vtr(vp + v_rd_off(D0, 0, 1)), l1 = vtr(vp + v_rd_off(D0, 1, 0)), h1 = vtr(vp + v_rd_off(D0, 1, 1));
;   const s16x4 l2 = vtr(vp + v_rd_off(D0, 2, 0)), h2 = vtr(vp + v_rd_off(D0, 2, 1)), l3 = vtr(vp + v_rd_off(D0, 3, 0)), h3 = vtr(vp + v_rd_off(D0, 3, 1));
;     ...
;   od = __builtin_amdgcn_mfma_f32_32x32x16_bf16(pa0, PK(l0, h0), od, 0, 0, 0);
;   od = __builtin_amdgcn_mfma_f32_32x32x16_bf16(pa1, PK(l1, h1), od, 0, 0, 0);
;   od = __builtin_amdgcn_mfma_f32_32x32x16_bf16(pa2, PK(l2, h2), od, 0, 0, 0);
.Lattn_f4:
	ds_read_b128 v[48:51], v243 offset:16384
	ds_read_b128 v[52:55], v243 offset:24576
	s_waitcnt lgkmcnt(1)
	v_mfma_f32_32x32x16_bf16 v[96:111], v[48:51], v[132:135], v[32:47]
	ds_read_b128 v[48:51], v244 offset:16384
	ds_read_b128 v[56:59], v244 offset:24576
	v_exp_f32_e32 v64, v64
	v_exp_f32_e32 v65, v65
	v_exp_f32_e32 v66, v66
	v_exp_f32_e32 v67, v67
	v_exp_f32_e32 v68, v68
	s_waitcnt lgkmcnt(2)
	v_mfma_f32_32x32x16_bf16 v[80:95], v[52:55], v[132:135], v[32:47]
	ds_read_b128 v[52:55], v245 offset:16384
	ds_read_b128 v[60:63], v245 offset:24576
	ds_read_b128 v[220:223], v246 offset:16384
	ds_read_b128 v[224:227], v246 offset:24576
	ds_read_b128 v[228:231], v247 offset:16384
	ds_read_b128 v[232:235], v247 offset:24576
	v_exp_f32_e32 v69, v69
	v_exp_f32_e32 v70, v70
	v_exp_f32_e32 v71, v71
	v_exp_f32_e32 v72, v72
	v_exp_f32_e32 v73, v73
	s_waitcnt lgkmcnt(7)
	v_mfma_f32_32x32x16_bf16 v[96:111], v[48:51], v[128:131], v[96:111]
	ds_read_b128 v[48:51], v248 offset:16384
	ds_read_b128 v[236:239], v248 offset:24576
	v_exp_f32_e32 v74, v74
	v_exp_f32_e32 v75, v75
	v_exp_f32_e32 v76, v76
	v_exp_f32_e32 v77, v77
	v_exp_f32_e32 v78, v78
	v_exp_f32_e32 v79, v79
	s_waitcnt lgkmcnt(8)
	v_mfma_f32_32x32x16_bf16 v[80:95], v[56:59], v[128:131], v[80:95]
	s_waitcnt lgkmcnt(7)
	v_mfma_f32_32x32x16_bf16 v[96:111], v[52:55], v[124:127], v[96:111]
	v_fma_f32 v52, v163, v152, v194
	v_add_f32_e32 v52, v216, v52
	v_add_f32_e32 v52, v192, v52
	v_add_f32_e32 v52, v195, v52
	v_add_f32_e32 v52, v190, v52
	v_add_f32_e32 v52, v193, v52
	v_add_f32_e32 v52, v189, v52
	s_waitcnt lgkmcnt(6)
	v_mfma_f32_32x32x16_bf16 v[80:95], v[60:63], v[124:127], v[80:95]
	v_add_f32_e32 v52, v191, v52
	v_add_f32_e32 v52, v186, v52
	v_add_f32_e32 v52, v188, v52
	v_add_f32_e32 v52, v185, v52
	v_add_f32_e32 v52, v187, v52
	v_add_f32_e32 v52, v181, v52
	v_add_f32_e32 v52, v183, v52
	s_waitcnt lgkmcnt(5)
	v_mfma_f32_32x32x16_bf16 v[96:111], v[220:223], v[120:123], v[96:111]
	v_add_f32_e32 v52, v180, v52
	v_add_f32_e32 v52, v182, v52
	v_add_f32_e32 v52, v64, v52
	v_add_f32_e32 v52, v65, v52
	v_add_f32_e32 v52, v66, v52
	v_add_f32_e32 v52, v67, v52
	v_add_f32_e32 v52, v68, v52
	s_waitcnt lgkmcnt(4)
	v_mfma_f32_32x32x16_bf16 v[80:95], v[224:227], v[120:123], v[80:95]
	v_add_f32_e32 v52, v69, v52
	v_add_f32_e32 v52, v70, v52
	v_add_f32_e32 v52, v71, v52
	v_add_f32_e32 v52, v72, v52
	v_add_f32_e32 v52, v73, v52
	v_add_f32_e32 v52, v74, v52
	v_add_f32_e32 v52, v75, v52
	s_waitcnt lgkmcnt(3)
	v_mfma_f32_32x32x16_bf16 v[96:111], v[228:231], v[116:119], v[96:111]
	v_add_f32_e32 v52, v76, v52
	v_add_f32_e32 v52, v77, v52
	v_add_f32_e32 v52, v78, v52
	v_add_f32_e32 v165, v79, v52
	s_waitcnt lgkmcnt(2)
	v_mfma_f32_32x32x16_bf16 v[80:95], v[232:235], v[116:119], v[80:95]
	v_cvt_pk_bf16_f32 v60, v194, v216
	v_cvt_pk_bf16_f32 v61, v192, v195
	v_cvt_pk_bf16_f32 v62, v190, v193
	v_cvt_pk_bf16_f32 v63, v189, v191
	v_cvt_pk_bf16_f32 v56, v186, v188
	v_cvt_pk_bf16_f32 v57, v185, v187
	v_cvt_pk_bf16_f32 v58, v181, v183
	s_waitcnt lgkmcnt(1)
	v_mfma_f32_32x32x16_bf16 v[96:111], v[48:51], v[112:115], v[96:111]
	v_cvt_pk_bf16_f32 v59, v180, v182
	v_cvt_pk_bf16_f32 v52, v64, v65
	v_cvt_pk_bf16_f32 v53, v66, v67
	v_cvt_pk_bf16_f32 v54, v68, v69
	v_cvt_pk_bf16_f32 v55, v70, v71
	v_cvt_pk_bf16_f32 v48, v72, v73
	v_cvt_pk_bf16_f32 v49, v74, v75
	s_waitcnt lgkmcnt(0)
	v_mfma_f32_32x32x16_bf16 v[80:95], v[236:239], v[112:115], v[80:95]
	v_cvt_pk_bf16_f32 v50, v76, v77
	v_cvt_pk_bf16_f32 v51, v78, v79
	s_waitcnt vmcnt(2)
	ds_write_b128 v204, v[144:147] offset:49152
	s_waitcnt vmcnt(1)
	ds_write_b128 v249, v[148:151] offset:49152
	s_waitcnt vmcnt(0)
	ds_write_b64 v250, v[174:175] offset:49152
	global_load_dwordx4 v[136:139], v240, s[98:99]
	global_load_dwordx4 v[140:143], v241, s[98:99]
	global_load_dwordx2 v[172:173], v242, s[100:101]
	s_add_u32 s98, s98, 0x10000
	s_addc_u32 s99, s99, 0
	s_add_u32 s100, s100, 0x1000
	s_addc_u32 s101, s101, 0
.Lf1_741:
	ds_read_b64_tr_b16 v[64:65], v203
	ds_read_b64_tr_b16 v[66:67], v203 offset:2048
	ds_read_b64_tr_b16 v[70:71], v203 offset:2560
	ds_read_b64_tr_b16 v[68:69], v203 offset:512
	s_waitcnt lgkmcnt(2)
	v_mfma_f32_32x32x16_bf16 v[0:15], v[60:63], v[64:67], v[0:15]
	ds_read_b64_tr_b16 v[64:65], v203 offset:4096
	ds_read_b64_tr_b16 v[66:67], v203 offset:6144
	ds_read_b64_tr_b16 v[74:75], v203 offset:6656
	ds_read_b64_tr_b16 v[72:73], v203 offset:4608
	s_waitcnt lgkmcnt(2)
	v_mfma_f32_32x32x16_bf16 v[0:15], v[56:59], v[64:67], v[0:15]
	ds_read_b64_tr_b16 v[64:65], v203 offset:8192
	ds_read_b64_tr_b16 v[66:67], v203 offset:10240
	ds_read_b64_tr_b16 v[78:79], v203 offset:10752
	ds_read_b64_tr_b16 v[76:77], v203 offset:8704
	v_mfma_f32_32x32x16_bf16 v[16:31], v[60:63], v[68:71], v[16:31]
	s_waitcnt lgkmcnt(2)
	v_mfma_f32_32x32x16_bf16 v[0:15], v[52:55], v[64:67], v[0:15]
	ds_read_b64_tr_b16 v[64:65], v203 offset:12288
	ds_read_b64_tr_b16 v[66:67], v203 offset:14336
	ds_read_b64_tr_b16 v[186:187], v203 offset:14848
	ds_read_b64_tr_b16 v[184:185], v203 offset:12800
	v_mfma_f32_32x32x16_bf16 v[16:31], v[56:59], v[72:75], v[16:31]
	s_waitcnt lgkmcnt(2)
	v_mfma_f32_32x32x16_bf16 v[0:15], v[48:51], v[64:67], v[0:15]
	v_max_f32_e32 v64, v96, v97
	v_max3_f32 v64, v64, v98, v99
	v_max3_f32 v60, v64, v100, v101
	v_max3_f32 v60, v60, v102, v103
	v_max3_f32 v60, v60, v104, v105
	v_max3_f32 v60, v60, v106, v107
	v_max3_f32 v60, v60, v108, v109
	v_mfma_f32_32x32x16_bf16 v[16:31], v[52:55], v[76:79], v[16:31]
	v_max3_f32 v60, v60, v110, v111
	v_max3_f32 v60, v60, v80, v81
	v_max3_f32 v56, v60, v82, v83
	v_max3_f32 v56, v56, v84, v85
	v_max3_f32 v56, v56, v86, v87
	v_max3_f32 v56, v56, v88, v89
	v_max3_f32 v56, v56, v90, v91
	v_max3_f32 v56, v56, v92, v93
	s_waitcnt lgkmcnt(0)
	v_mfma_f32_32x32x16_bf16 v[16:31], v[48:51], v[184:187], v[16:31]
	v_max3_f32 v56, v56, v94, v95
	v_cmp_ge_f32_e32 vcc, s86, v56
	s_cmp_eq_u64 vcc, exec
	s_cbranch_scc0 .Lf1_757
	v_mov_b32_e32 v169, 1.0
; #define PK4(P, BASE, OUT) do { u32x4 w = {cvt_pk_bf16(P[BASE + 0], P[BASE + 1]), cvt_pk_bf16(P[BASE + 2], P[BASE + 3]), cvt_pk_bf16(P[BASE + 4], P[BASE + 5]), cvt_pk_bf16(P[BASE + 6], P[BASE + 7])}; \
;     OUT = *reinterpret_cast<bf16x8*>(&w); } while (0)
; __device__ __forceinline__ void finishSM(f32x16& p0, f32x16& p1, float alpha, float& l_reg, bf16x8& pa0, bf16x8& pa1, bf16x8& pa2, bf16x8& pa3) {
; #pragma unroll
;   for (int r = 0; r < 16; ++r) p1[r] = __builtin_amdgcn_exp2f(p1[r]);
;   float ps = 0;
; #pragma unroll
;   for (int r = 0; r < 16; ++r) ps += p0[r];
; #pragma unroll
;   for (int r = 0; r < 16; ++r) ps += p1[r];
;   { auto rr = __builtin_amdgcn_permlane32_swap(__float_as_uint(ps), __float_as_uint(ps), false, false);
;     ps = __uint_as_float(rr[0]) + __uint_as_float(rr[1]); }
;   l_reg = l_reg * alpha + ps;
;     ...
;   PK4(p0, 0, pa0); PK4(p0, 8, pa1); PK4(p1, 0, pa2); PK4(p1, 8, pa3);
;     ...
; }
; __device__ __forceinline__ void qkt(f32x16& p0, f32x16& p1, const char* Ks, const bf16x8* qr, const f32x16& negm, int r32, int hi) {
;   p0 = negm; p1 = negm;
; #pragma unroll
;   for (int d0 = 0; d0 < 6; ++d0) { int cb = (d0 * 16 + hi * 8) * 2;
;     bf16x8 b0 = *reinterpret_cast<const bf16x8*>(Ks + KSWZ(r32, cb));
;     bf16x8 b1 = *reinterpret_cast<const bf16x8*>(Ks + KSWZ(32 + r32, cb));
;     p0 = __builtin_amdgcn_mfma_f32_32x32x16_bf16(b0, qr[d0], p0, 0, 0, 0);
;     p1 = __builtin_amdgcn_mfma_f32_32x32x16_bf16(b1, qr[d0], p1, 0, 0, 0); }
; }
.Lf1_746:
	s_waitcnt lgkmcnt(0)
	s_barrier
	ds_read_b128 v[64:67], v243 offset:32768
	ds_read_b128 v[184:187], v243 offset:40960
	v_exp_f32_e32 v192, v96
	v_exp_f32_e32 v193, v97
	v_exp_f32_e32 v194, v98
	v_exp_f32_e32 v195, v99
	v_exp_f32_e32 v216, v100
	v_exp_f32_e32 v217, v101
	v_exp_f32_e32 v219, v102
	v_exp_f32_e32 v220, v103
	v_exp_f32_e32 v221, v104
	v_exp_f32_e32 v222, v105
	v_exp_f32_e32 v223, v106
	v_exp_f32_e32 v224, v107
	v_exp_f32_e32 v225, v108
	v_exp_f32_e32 v226, v109
	v_exp_f32_e32 v227, v110
	v_exp_f32_e32 v228, v111
	v_exp_f32_e32 v80, v80
	v_exp_f32_e32 v81, v81
	s_waitcnt lgkmcnt(1)
	v_mfma_f32_32x32x16_bf16 v[96:111], v[64:67], v[132:135], v[32:47]
	v_exp_f32_e32 v82, v82
	v_exp_f32_e32 v83, v83
	v_exp_f32_e32 v87, v87
	v_exp_f32_e32 v229, v92
	v_exp_f32_e32 v230, v93
	v_exp_f32_e32 v231, v94
	v_exp_f32_e32 v232, v95
	s_waitcnt lgkmcnt(0)
	v_mfma_f32_32x32x16_bf16 v[64:79], v[184:187], v[132:135], v[32:47]
	ds_read_b128 v[184:187], v244 offset:32768
	ds_read_b128 v[188:191], v244 offset:40960
	s_waitcnt lgkmcnt(1)
	v_mfma_f32_32x32x16_bf16 v[96:111], v[184:187], v[128:131], v[96:111]
	s_waitcnt lgkmcnt(0)
	v_mfma_f32_32x32x16_bf16 v[64:79], v[188:191], v[128:131], v[64:79]
	ds_read_b128 v[184:187], v245 offset:32768
	ds_read_b128 v[188:191], v245 offset:40960
	s_waitcnt lgkmcnt(1)
	v_mfma_f32_32x32x16_bf16 v[96:111], v[184:187], v[124:127], v[96:111]
	s_waitcnt lgkmcnt(0)
	v_mfma_f32_32x32x16_bf16 v[64:79], v[188:191], v[124:127], v[64:79]
	ds_read_b128 v[184:187], v246 offset:32768
	ds_read_b128 v[188:191], v246 offset:40960
	s_waitcnt lgkmcnt(1)
	v_mfma_f32_32x32x16_bf16 v[96:111], v[184:187], v[120:123], v[96:111]
	s_waitcnt lgkmcnt(0)
	v_mfma_f32_32x32x16_bf16 v[64:79], v[188:191], v[120:123], v[64:79]
	ds_read_b128 v[184:187], v247 offset:32768
	ds_read_b128 v[188:191], v247 offset:40960
	s_waitcnt lgkmcnt(1)
	v_mfma_f32_32x32x16_bf16 v[96:111], v[184:187], v[116:119], v[96:111]
	s_waitcnt lgkmcnt(0)
	v_mfma_f32_32x32x16_bf16 v[64:79], v[188:191], v[116:119], v[64:79]
	ds_read_b128 v[184:187], v248 offset:32768
	ds_read_b128 v[188:191], v248 offset:40960
	v_cvt_pk_bf16_f32 v92, v192, v193
	v_cvt_pk_bf16_f32 v93, v194, v195
	v_cvt_pk_bf16_f32 v94, v216, v217
	v_cvt_pk_bf16_f32 v95, v219, v220
	s_waitcnt lgkmcnt(1)
	v_mfma_f32_32x32x16_bf16 v[96:111], v[184:187], v[112:115], v[96:111]
	v_exp_f32_e32 v185, v84
	v_fma_f32 v84, v165, v169, v192
	v_add_f32_e32 v84, v193, v84
	v_add_f32_e32 v84, v194, v84
	v_add_f32_e32 v84, v195, v84
	v_add_f32_e32 v84, v216, v84
	v_add_f32_e32 v84, v217, v84
	v_add_f32_e32 v84, v219, v84
	v_add_f32_e32 v84, v220, v84
	v_add_f32_e32 v84, v221, v84
	v_add_f32_e32 v84, v222, v84
	v_add_f32_e32 v84, v223, v84
	v_add_f32_e32 v84, v224, v84
	v_add_f32_e32 v84, v225, v84
	v_add_f32_e32 v84, v226, v84
	v_add_f32_e32 v84, v227, v84
	v_add_f32_e32 v84, v228, v84
	v_add_f32_e32 v84, v80, v84
	v_exp_f32_e32 v186, v85
	v_add_f32_e32 v84, v81, v84
	v_exp_f32_e32 v187, v86
	v_add_f32_e32 v84, v82, v84
	v_add_f32_e32 v84, v83, v84
	s_waitcnt lgkmcnt(0)
	v_mfma_f32_32x32x16_bf16 v[64:79], v[188:191], v[112:115], v[64:79]
	v_exp_f32_e32 v188, v88
	v_add_f32_e32 v84, v185, v84
	v_exp_f32_e32 v189, v89
	v_add_f32_e32 v84, v186, v84
	v_exp_f32_e32 v190, v90
	v_add_f32_e32 v84, v187, v84
	v_exp_f32_e32 v191, v91
	v_add_f32_e32 v84, v87, v84
	v_add_f32_e32 v84, v188, v84
	v_add_f32_e32 v84, v189, v84
	v_add_f32_e32 v84, v190, v84
	v_add_f32_e32 v84, v191, v84
	v_add_f32_e32 v84, v229, v84
	v_add_f32_e32 v84, v230, v84
	v_add_f32_e32 v84, v231, v84
	v_add_f32_e32 v152, v232, v84
	v_cvt_pk_bf16_f32 v88, v221, v222
	v_cvt_pk_bf16_f32 v89, v223, v224
	v_cvt_pk_bf16_f32 v90, v225, v226
	v_cvt_pk_bf16_f32 v91, v227, v228
	v_cvt_pk_bf16_f32 v84, v80, v81
	v_cvt_pk_bf16_f32 v85, v82, v83
	v_cvt_pk_bf16_f32 v86, v185, v186
	v_cvt_pk_bf16_f32 v87, v187, v87
	v_cvt_pk_bf16_f32 v80, v188, v189
	v_cvt_pk_bf16_f32 v81, v190, v191
	v_cvt_pk_bf16_f32 v82, v229, v230
	v_cvt_pk_bf16_f32 v83, v231, v232
	s_waitcnt vmcnt(2)
	ds_write_b128 v204, v[136:139]
	s_waitcnt vmcnt(1)
	ds_write_b128 v249, v[140:143]
	s_waitcnt vmcnt(0)
	ds_write_b64 v250, v[172:173]

; #define PK4(P, BASE, OUT) do { u32x4 w = {cvt_pk_bf16(P[BASE + 0], P[BASE + 1]), cvt_pk_bf16(P[BASE + 2], P[BASE + 3]), cvt_pk_bf16(P[BASE + 4], P[BASE + 5]), cvt_pk_bf16(P[BASE + 6], P[BASE + 7])}; \
;     OUT = *reinterpret_cast<bf16x8*>(&w); } while (0)
; template <bool FIRST> __device__ __forceinline__ void partialSM(f32x16& p0, f32x16& p1, float& mref, f32x16& negm, float& alpha) {
;     ...
;   for (int r = 0; r < 16; ++r) p0[r] = __builtin_amdgcn_exp2f(p0[r]);
; }
; __device__ __forceinline__ void finishSM(f32x16& p0, f32x16& p1, float alpha, float& l_reg, bf16x8& pa0, bf16x8& pa1, bf16x8& pa2, bf16x8& pa3) {
; #pragma unroll
;   for (int r = 0; r < 16; ++r) p1[r] = __builtin_amdgcn_exp2f(p1[r]);
;   float ps = 0;
; #pragma unroll
;   for (int r = 0; r < 16; ++r) ps += p0[r];
; #pragma unroll
;   for (int r = 0; r < 16; ++r) ps += p1[r];
;   { auto rr = __builtin_amdgcn_permlane32_swap(__float_as_uint(ps), __float_as_uint(ps), false, false);
;     ps = __uint_as_float(rr[0]) + __uint_as_float(rr[1]); }
;   l_reg = l_reg * alpha + ps;
;     ...
;   PK4(p0, 0, pa0); PK4(p0, 8, pa1); PK4(p1, 0, pa2); PK4(p1, 8, pa3);
;     ...
; }
; __device__ __forceinline__ void qkt(f32x16& p0, f32x16& p1, const char* Ks, const bf16x8* qr, const f32x16& negm, int r32, int hi) {
;   p0 = negm; p1 = negm;
; #pragma unroll
;   for (int d0 = 0; d0 < 6; ++d0) { int cb = (d0 * 16 + hi * 8) * 2;
;     bf16x8 b0 = *reinterpret_cast<const bf16x8*>(Ks + KSWZ(r32, cb));
;     bf16x8 b1 = *reinterpret_cast<const bf16x8*>(Ks + KSWZ(32 + r32, cb));
;     p0 = __builtin_amdgcn_mfma_f32_32x32x16_bf16(b0, qr[d0], p0, 0, 0, 0);
;     p1 = __builtin_amdgcn_mfma_f32_32x32x16_bf16(b1, qr[d0], p1, 0, 0, 0); }
; }
.Lf1_755:
	v_exp_f32_e32 v194, v96
	v_exp_f32_e32 v216, v97
	v_exp_f32_e32 v192, v98
	v_exp_f32_e32 v195, v99
	v_exp_f32_e32 v190, v100
	v_exp_f32_e32 v193, v101
	v_exp_f32_e32 v189, v102
	v_exp_f32_e32 v191, v103
	v_exp_f32_e32 v186, v104
	v_exp_f32_e32 v188, v105
	v_exp_f32_e32 v185, v106
	v_exp_f32_e32 v187, v107
	v_exp_f32_e32 v181, v108
	v_exp_f32_e32 v183, v109
	v_exp_f32_e32 v180, v110
	v_exp_f32_e32 v182, v111
	s_add_i32 s90, s90, 2
	s_add_i32 s89, s89, 0x8000
	v_mov_b32_e32 v163, v84
	s_waitcnt lgkmcnt(0)
	s_barrier
	ds_read_b128 v[48:51], v243 offset:49152
	ds_read_b128 v[52:55], v243 offset:57344
	s_waitcnt lgkmcnt(1)
	v_mfma_f32_32x32x16_bf16 v[96:111], v[48:51], v[132:135], v[32:47]
	ds_read_b128 v[48:51], v244 offset:49152
	ds_read_b128 v[56:59], v244 offset:57344
	v_exp_f32_e32 v64, v64
	v_exp_f32_e32 v65, v65
	v_exp_f32_e32 v66, v66
	v_exp_f32_e32 v67, v67
	v_exp_f32_e32 v68, v68
	s_waitcnt lgkmcnt(2)
	v_mfma_f32_32x32x16_bf16 v[80:95], v[52:55], v[132:135], v[32:47]
	ds_read_b128 v[52:55], v245 offset:49152
	ds_read_b128 v[60:63], v245 offset:57344
	ds_read_b128 v[220:223], v246 offset:49152
	ds_read_b128 v[224:227], v246 offset:57344
	ds_read_b128 v[228:231], v247 offset:49152
	ds_read_b128 v[232:235], v247 offset:57344
	v_exp_f32_e32 v69, v69
	v_exp_f32_e32 v70, v70
	v_exp_f32_e32 v71, v71
	v_exp_f32_e32 v72, v72
	v_exp_f32_e32 v73, v73
	s_waitcnt lgkmcnt(7)
	v_mfma_f32_32x32x16_bf16 v[96:111], v[48:51], v[128:131], v[96:111]
	ds_read_b128 v[48:51], v248 offset:49152
	ds_read_b128 v[236:239], v248 offset:57344
	v_exp_f32_e32 v74, v74
	v_exp_f32_e32 v75, v75
	v_exp_f32_e32 v76, v76
	v_exp_f32_e32 v77, v77
	v_exp_f32_e32 v78, v78
	v_exp_f32_e32 v79, v79
	s_waitcnt lgkmcnt(8)
	v_mfma_f32_32x32x16_bf16 v[80:95], v[56:59], v[128:131], v[80:95]
	s_waitcnt lgkmcnt(7)
	v_mfma_f32_32x32x16_bf16 v[96:111], v[52:55], v[124:127], v[96:111]
	v_fma_f32 v52, v163, v152, v194
	v_add_f32_e32 v52, v216, v52
	v_add_f32_e32 v52, v192, v52
	v_add_f32_e32 v52, v195, v52
	v_add_f32_e32 v52, v190, v52
	v_add_f32_e32 v52, v193, v52
	v_add_f32_e32 v52, v189, v52
	s_waitcnt lgkmcnt(6)
	v_mfma_f32_32x32x16_bf16 v[80:95], v[60:63], v[124:127], v[80:95]
	v_add_f32_e32 v52, v191, v52
	v_add_f32_e32 v52, v186, v52
	v_add_f32_e32 v52, v188, v52
	v_add_f32_e32 v52, v185, v52
	v_add_f32_e32 v52, v187, v52
	v_add_f32_e32 v52, v181, v52
	v_add_f32_e32 v52, v183, v52
	s_waitcnt lgkmcnt(5)
	v_mfma_f32_32x32x16_bf16 v[96:111], v[220:223], v[120:123], v[96:111]
	v_add_f32_e32 v52, v180, v52
	v_add_f32_e32 v52, v182, v52
	v_add_f32_e32 v52, v64, v52
	v_add_f32_e32 v52, v65, v52
	v_add_f32_e32 v52, v66, v52
	v_add_f32_e32 v52, v67, v52
	v_add_f32_e32 v52, v68, v52
	s_waitcnt lgkmcnt(4)
	v_mfma_f32_32x32x16_bf16 v[80:95], v[224:227], v[120:123], v[80:95]
	v_add_f32_e32 v52, v69, v52
	v_add_f32_e32 v52, v70, v52
	v_add_f32_e32 v52, v71, v52
	v_add_f32_e32 v52, v72, v52
	v_add_f32_e32 v52, v73, v52
	v_add_f32_e32 v52, v74, v52
	v_add_f32_e32 v52, v75, v52
	s_waitcnt lgkmcnt(3)
	v_mfma_f32_32x32x16_bf16 v[96:111], v[228:231], v[116:119], v[96:111]
	v_add_f32_e32 v52, v76, v52
	v_add_f32_e32 v52, v77, v52
	v_add_f32_e32 v52, v78, v52
	v_add_f32_e32 v165, v79, v52
	s_waitcnt lgkmcnt(2)
	v_mfma_f32_32x32x16_bf16 v[80:95], v[232:235], v[116:119], v[80:95]
	v_cvt_pk_bf16_f32 v60, v194, v216
	v_cvt_pk_bf16_f32 v61, v192, v195
	v_cvt_pk_bf16_f32 v62, v190, v193
	v_cvt_pk_bf16_f32 v63, v189, v191
	v_cvt_pk_bf16_f32 v56, v186, v188
	v_cvt_pk_bf16_f32 v57, v185, v187
	v_cvt_pk_bf16_f32 v58, v181, v183
	s_waitcnt lgkmcnt(1)
	v_mfma_f32_32x32x16_bf16 v[96:111], v[48:51], v[112:115], v[96:111]
	v_cvt_pk_bf16_f32 v59, v180, v182
	v_cvt_pk_bf16_f32 v52, v64, v65
	v_cvt_pk_bf16_f32 v53, v66, v67
	v_cvt_pk_bf16_f32 v54, v68, v69
	v_cvt_pk_bf16_f32 v55, v70, v71
	v_cvt_pk_bf16_f32 v48, v72, v73
	v_cvt_pk_bf16_f32 v49, v74, v75
	s_waitcnt lgkmcnt(0)
	v_mfma_f32_32x32x16_bf16 v[80:95], v[236:239], v[112:115], v[80:95]
	v_cvt_pk_bf16_f32 v50, v76, v77
	v_cvt_pk_bf16_f32 v51, v78, v79
	s_waitcnt vmcnt(2)
	ds_write_b128 v204, v[144:147] offset:16384
	s_waitcnt vmcnt(1)
	ds_write_b128 v249, v[148:151] offset:16384
	s_waitcnt vmcnt(0)
	ds_write_b64 v250, v[174:175] offset:16384
	global_load_dwordx4 v[136:139], v240, s[98:99]
	global_load_dwordx4 v[140:143], v241, s[98:99]
	global_load_dwordx2 v[172:173], v242, s[100:101]
	s_add_u32 s98, s98, 0x10000
	s_addc_u32 s99, s99, 0
	s_add_u32 s100, s100, 0x1000
	s_addc_u32 s101, s101, 0
; template <bool FIRST> __device__ __forceinline__ void partialSM(f32x16& p0, f32x16& p1, float& mref, f32x16& negm, float& alpha) {
;   constexpr float THRL = THR * 1.4426950408889634f;
;   float pmax = p0[0];
; #pragma unroll
;   for (int r = 1; r < 16; ++r) pmax = fmaxf(pmax, p0[r]);
; #pragma unroll
;   for (int r = 0; r < 16; ++r) pmax = fmaxf(pmax, p1[r]);
;   { auto rr = __builtin_amdgcn_permlane32_swap(__float_as_uint(pmax), __float_as_uint(pmax), false, false);
;     pmax = fmaxf(__uint_as_float(rr[0]), __uint_as_float(rr[1])); }
;   if (!FIRST && __builtin_expect(__all(pmax <= THRL), 1)) { alpha = 1.f; }
;   else { const float dl = FIRST ? pmax : fmaxf(pmax, 0.f); mref += dl; alpha = FIRST ? 1.f : __builtin_amdgcn_exp2f(-dl);
; #pragma unroll
;     for (int r = 0; r < 16; ++r) { p0[r] -= dl; p1[r] -= dl; }
;     const float nm = -mref;
; #pragma unroll
;     for (int r = 0; r < 16; ++r) negm[r] = nm; }
; #pragma unroll
;   for (int r = 0; r < 16; ++r) p0[r] = __builtin_amdgcn_exp2f(p0[r]);
; }
; __device__ __forceinline__ void finishSM(f32x16& p0, f32x16& p1, float alpha, float& l_reg, bf16x8& pa0, bf16x8& pa1, bf16x8& pa2, bf16x8& pa3) {
; #pragma unroll
;   for (int r = 0; r < 16; ++r) p1[r] = __builtin_amdgcn_exp2f(p1[r]);
;   float ps = 0;
; #pragma unroll
;   for (int r = 0; r < 16; ++r) ps += p0[r];
; #pragma unroll
;   for (int r = 0; r < 16; ++r) ps += p1[r];
;   { auto rr = __builtin_amdgcn_permlane32_swap(__float_as_uint(ps), __float_as_uint(ps), false, false);
;     ps = __uint_as_float(rr[0]) + __uint_as_float(rr[1]); }
;   l_reg = l_reg * alpha + ps;
;     ...
;   PK4(p0, 0, pa0); PK4(p0, 8, pa1); PK4(p1, 0, pa2); PK4(p1, 8, pa3);
;     ...
; }
; __device__ __forceinline__ void qkt(f32x16& p0, f32x16& p1, const char* Ks, const bf16x8* qr, const f32x16& negm, int r32, int hi) {
;   p0 = negm; p1 = negm;
; #pragma unroll
;   for (int d0 = 0; d0 < 6; ++d0) { int cb = (d0 * 16 + hi * 8) * 2;
;     bf16x8 b0 = *reinterpret_cast<const bf16x8*>(Ks + KSWZ(r32, cb));
;     bf16x8 b1 = *reinterpret_cast<const bf16x8*>(Ks + KSWZ(32 + r32, cb));
;     p0 = __builtin_amdgcn_mfma_f32_32x32x16_bf16(b0, qr[d0], p0, 0, 0, 0);
;     p1 = __builtin_amdgcn_mfma_f32_32x32x16_bf16(b1, qr[d0], p1, 0, 0, 0); }
; }
; template <int D0> __device__ __forceinline__ void pv_one(f32x16& od, lds_cptr vp, bf16x8 pa0, bf16x8 pa1, bf16x8 pa2, bf16x8 pa3) {
.Lf2_741:
	ds_read_b64_tr_b16 v[64:65], v203 offset:32768
	ds_read_b64_tr_b16 v[66:67], v203 offset:34816
	ds_read_b64_tr_b16 v[70:71], v203 offset:35328
	ds_read_b64_tr_b16 v[68:69], v203 offset:33280
	s_waitcnt lgkmcnt(2)
	v_mfma_f32_32x32x16_bf16 v[0:15], v[60:63], v[64:67], v[0:15]
	ds_read_b64_tr_b16 v[64:65], v203 offset:36864
	ds_read_b64_tr_b16 v[66:67], v203 offset:38912
	ds_read_b64_tr_b16 v[74:75], v203 offset:39424
	ds_read_b64_tr_b16 v[72:73], v203 offset:37376
	s_waitcnt lgkmcnt(2)
	v_mfma_f32_32x32x16_bf16 v[0:15], v[56:59], v[64:67], v[0:15]
	ds_read_b64_tr_b16 v[64:65], v203 offset:40960
	ds_read_b64_tr_b16 v[66:67], v203 offset:43008
	ds_read_b64_tr_b16 v[78:79], v203 offset:43520
	ds_read_b64_tr_b16 v[76:77], v203 offset:41472
	v_mfma_f32_32x32x16_bf16 v[16:31], v[60:63], v[68:71], v[16:31]
	s_waitcnt lgkmcnt(2)
	v_mfma_f32_32x32x16_bf16 v[0:15], v[52:55], v[64:67], v[0:15]
	ds_read_b64_tr_b16 v[64:65], v203 offset:45056
	ds_read_b64_tr_b16 v[66:67], v203 offset:47104
	ds_read_b64_tr_b16 v[186:187], v203 offset:47616
	ds_read_b64_tr_b16 v[184:185], v203 offset:45568
	v_mfma_f32_32x32x16_bf16 v[16:31], v[56:59], v[72:75], v[16:31]
	s_waitcnt lgkmcnt(2)
	v_mfma_f32_32x32x16_bf16 v[0:15], v[48:51], v[64:67], v[0:15]
	v_max_f32_e32 v64, v96, v97
	v_max3_f32 v64, v64, v98, v99
	v_max3_f32 v60, v64, v100, v101
	v_max3_f32 v60, v60, v102, v103
	v_max3_f32 v60, v60, v104, v105
	v_max3_f32 v60, v60, v106, v107
	v_max3_f32 v60, v60, v108, v109
	v_mfma_f32_32x32x16_bf16 v[16:31], v[52:55], v[76:79], v[16:31]
	v_max3_f32 v60, v60, v110, v111
	v_max3_f32 v60, v60, v80, v81
	v_max3_f32 v56, v60, v82, v83
	v_max3_f32 v56, v56, v84, v85
	v_max3_f32 v56, v56, v86, v87
	v_max3_f32 v56, v56, v88, v89
	v_max3_f32 v56, v56, v90, v91
	v_max3_f32 v56, v56, v92, v93
	s_waitcnt lgkmcnt(0)
	v_mfma_f32_32x32x16_bf16 v[16:31], v[48:51], v[184:187], v[16:31]
	v_max3_f32 v56, v56, v94, v95
	v_cmp_ge_f32_e32 vcc, s86, v56
	s_cmp_eq_u64 vcc, exec
	s_cbranch_scc0 .Lf2_757
	v_mov_b32_e32 v169, 1.0
.Lf2_746:
	s_waitcnt lgkmcnt(0)
	s_barrier
	ds_read_b128 v[64:67], v243
	ds_read_b128 v[184:187], v243 offset:8192
	v_exp_f32_e32 v192, v96
	v_exp_f32_e32 v193, v97
	v_exp_f32_e32 v194, v98
	v_exp_f32_e32 v195, v99
	v_exp_f32_e32 v216, v100
	v_exp_f32_e32 v217, v101
	v_exp_f32_e32 v219, v102
	v_exp_f32_e32 v220, v103
	v_exp_f32_e32 v221, v104
	v_exp_f32_e32 v222, v105
	v_exp_f32_e32 v223, v106
	v_exp_f32_e32 v224, v107
	v_exp_f32_e32 v225, v108
	v_exp_f32_e32 v226, v109
	v_exp_f32_e32 v227, v110
	v_exp_f32_e32 v228, v111
	v_exp_f32_e32 v80, v80
	v_exp_f32_e32 v81, v81
	s_waitcnt lgkmcnt(1)
	v_mfma_f32_32x32x16_bf16 v[96:111], v[64:67], v[132:135], v[32:47]
	v_exp_f32_e32 v82, v82
	v_exp_f32_e32 v83, v83
	v_exp_f32_e32 v87, v87
	v_exp_f32_e32 v229, v92
	v_exp_f32_e32 v230, v93
	v_exp_f32_e32 v231, v94
	v_exp_f32_e32 v232, v95
	s_waitcnt lgkmcnt(0)
	v_mfma_f32_32x32x16_bf16 v[64:79], v[184:187], v[132:135], v[32:47]
	ds_read_b128 v[184:187], v244
	ds_read_b128 v[188:191], v244 offset:8192
	s_waitcnt lgkmcnt(1)
	v_mfma_f32_32x32x16_bf16 v[96:111], v[184:187], v[128:131], v[96:111]
	s_waitcnt lgkmcnt(0)
	v_mfma_f32_32x32x16_bf16 v[64:79], v[188:191], v[128:131], v[64:79]
	ds_read_b128 v[184:187], v245
	ds_read_b128 v[188:191], v245 offset:8192
	s_waitcnt lgkmcnt(1)
	v_mfma_f32_32x32x16_bf16 v[96:111], v[184:187], v[124:127], v[96:111]
	s_waitcnt lgkmcnt(0)
	v_mfma_f32_32x32x16_bf16 v[64:79], v[188:191], v[124:127], v[64:79]
	ds_read_b128 v[184:187], v246
	ds_read_b128 v[188:191], v246 offset:8192
	s_waitcnt lgkmcnt(1)
	v_mfma_f32_32x32x16_bf16 v[96:111], v[184:187], v[120:123], v[96:111]
	s_waitcnt lgkmcnt(0)
	v_mfma_f32_32x32x16_bf16 v[64:79], v[188:191], v[120:123], v[64:79]
	ds_read_b128 v[184:187], v247
	ds_read_b128 v[188:191], v247 offset:8192
	s_waitcnt lgkmcnt(1)
	v_mfma_f32_32x32x16_bf16 v[96:111], v[184:187], v[116:119], v[96:111]
	s_waitcnt lgkmcnt(0)
	v_mfma_f32_32x32x16_bf16 v[64:79], v[188:191], v[116:119], v[64:79]
	ds_read_b128 v[184:187], v248
	ds_read_b128 v[188:191], v248 offset:8192
	v_cvt_pk_bf16_f32 v92, v192, v193
	v_cvt_pk_bf16_f32 v93, v194, v195
	v_cvt_pk_bf16_f32 v94, v216, v217
	v_cvt_pk_bf16_f32 v95, v219, v220
	s_waitcnt lgkmcnt(1)
	v_mfma_f32_32x32x16_bf16 v[96:111], v[184:187], v[112:115], v[96:111]
	v_exp_f32_e32 v185, v84
	v_fma_f32 v84, v165, v169, v192
	v_add_f32_e32 v84, v193, v84
	v_add_f32_e32 v84, v194, v84
	v_add_f32_e32 v84, v195, v84
	v_add_f32_e32 v84, v216, v84
	v_add_f32_e32 v84, v217, v84
	v_add_f32_e32 v84, v219, v84
	v_add_f32_e32 v84, v220, v84
	v_add_f32_e32 v84, v221, v84
	v_add_f32_e32 v84, v222, v84
	v_add_f32_e32 v84, v223, v84
	v_add_f32_e32 v84, v224, v84
	v_add_f32_e32 v84, v225, v84
	v_add_f32_e32 v84, v226, v84
	v_add_f32_e32 v84, v227, v84
	v_add_f32_e32 v84, v228, v84
	v_add_f32_e32 v84, v80, v84
	v_exp_f32_e32 v186, v85
	v_add_f32_e32 v84, v81, v84
	v_exp_f32_e32 v187, v86
	v_add_f32_e32 v84, v82, v84
	v_add_f32_e32 v84, v83, v84
	s_waitcnt lgkmcnt(0)
	v_mfma_f32_32x32x16_bf16 v[64:79], v[188:191], v[112:115], v[64:79]
	v_exp_f32_e32 v188, v88
	v_add_f32_e32 v84, v185, v84
	v_exp_f32_e32 v189, v89
	v_add_f32_e32 v84, v186, v84
	v_exp_f32_e32 v190, v90
	v_add_f32_e32 v84, v187, v84
	v_exp_f32_e32 v191, v91
	v_add_f32_e32 v84, v87, v84
	v_add_f32_e32 v84, v188, v84
	v_add_f32_e32 v84, v189, v84
	v_add_f32_e32 v84, v190, v84
	v_add_f32_e32 v84, v191, v84
	v_add_f32_e32 v84, v229, v84
	v_add_f32_e32 v84, v230, v84
	v_add_f32_e32 v84, v231, v84
	v_add_f32_e32 v152, v232, v84
	v_cvt_pk_bf16_f32 v88, v221, v222
	v_cvt_pk_bf16_f32 v89, v223, v224
	v_cvt_pk_bf16_f32 v90, v225, v226
	v_cvt_pk_bf16_f32 v91, v227, v228
	v_cvt_pk_bf16_f32 v84, v80, v81
	v_cvt_pk_bf16_f32 v85, v82, v83
	v_cvt_pk_bf16_f32 v86, v185, v186
	v_cvt_pk_bf16_f32 v87, v187, v87
	v_cvt_pk_bf16_f32 v80, v188, v189
	v_cvt_pk_bf16_f32 v81, v190, v191
	v_cvt_pk_bf16_f32 v82, v229, v230
	v_cvt_pk_bf16_f32 v83, v231, v232
	s_waitcnt vmcnt(2)
	ds_write_b128 v204, v[136:139] offset:32768
	s_waitcnt vmcnt(1)
	ds_write_b128 v249, v[140:143] offset:32768
	s_waitcnt vmcnt(0)
	ds_write_b64 v250, v[172:173] offset:32768
